# phaseA k-loop: scalar m0 + saddr LDS-DMA, ds_reads first, counted lgkmcnt
# speedup vs baseline: 1.0121x; 1.0121x over previous
; DI int tidx() { int t = __builtin_amdgcn_workitem_id_x(); asm volatile("" : "+v"(t)); return t; }
; #define MFMA16(a, b, c) __builtin_amdgcn_mfma_f32_16x16x32_bf16((a), (b), (c), 0, 0, 0)
; DI void gemm_tile(const bf16_t* __restrict__ A, int lda, const bf16_t* __restrict__ Bt, int ldb, int bvalid, int K, f32x4 (&acc)[4][4], char* lds, bool preloaded = false) {
;     ...
;   const bf16_t* ap = A + (size_t)lr * lda + ((lc ^ ((lr >> 1) & 7)) << 3);
;   const bf16_t* bp = Bt + ((lc ^ ((lr >> 1) & 7)) << 3);
;   typedef __attribute__((address_space(1))) const unsigned gptr_t;
;   typedef __attribute__((address_space(3))) unsigned lptr_t;
;   const unsigned lbase = (unsigned)(size_t)lds + (unsigned)tid * 16u;
;     ...
;   auto compute = [&](int st) {
;     const char* base = lds + st * 32768;
;     bf16x8 af[2][4], bfr[2][4];
; #pragma unroll
;     for (int s = 0; s < 2; ++s) {
;       const int ch = ((4 * s + fq) ^ fx) << 4;
; #pragma unroll
;       for (int mi = 0; mi < 4; ++mi) af[s][mi] = *(const bf16x8*)(base + (wm * 64 + mi * 16 + fr) * 128 + ch);
; #pragma unroll
;       for (int ni = 0; ni < 4; ++ni) bfr[s][ni] = *(const bf16x8*)(base + 16384 + (wn * 64 + ni * 16 + fr) * 128 + ch);
;     }
;     __builtin_amdgcn_s_setprio(1);
; #pragma unroll
;     for (int s = 0; s < 2; ++s)
; #pragma unroll
;       for (int mi = 0; mi < 4; ++mi)
; #pragma unroll
;         for (int ni = 0; ni < 4; ++ni) acc[mi][ni] = MFMA16(af[s][mi], bfr[s][ni], acc[mi][ni]);
;     __builtin_amdgcn_s_setprio(0);
;   };
;   const int nk = K >> 6;
;   if (!preloaded) { GLDS(0, 0) }
; DI void phaseA_tile(const P& p, int layer, int mt, int nt, char* lds) {
;   const int tid = tidx(), lane = tid & 63, wave = __builtin_amdgcn_readfirstlane(tid >> 6);
;   const int row0 = mt * 128, col0 = nt * 128;
;   const int bvalid = (NP - col0) < 128 ? 64 : 128;
;   float* rr = (float*)(lds + RR_OFF);
;   __syncthreads();
;   const float* sp = (const float*)(p.ws + W_SS) + (size_t)(row0 + (tid & 127)) * 16;
;   const f32x4 ssa = *(const f32x4*)sp, ssb = *(const f32x4*)(sp + 4), ssc = *(const f32x4*)(sp + 8), ssd = *(const f32x4*)(sp + 12);
;   f32x4 acc[4][4];
;   zero_acc(acc);
;   gemm_tile((const bf16_t*)(p.ws + W_XB) + (size_t)row0 * DM, DM, (const bf16_t*)(p.ws + W_WIN) + ((size_t)layer * NP + col0) * 1024, 1024, bvalid, 1024, acc, lds);
.LBB0_1192:
	s_lshl_b32 s10, s36, 7
	s_ashr_i32 s11, s10, 31
	v_mov_b32_e32 v92, v158
	s_lshl_b32 s0, s37, 7
	s_lshl_b64 s[4:5], s[10:11], 11
	s_add_u32 s12, s74, s4
	v_and_b32_e32 v0, 0x7f, v92
	s_addc_u32 s13, s75, s5
	s_ashr_i32 s1, s0, 31
	v_or_b32_e32 v2, s10, v0
	s_add_u32 s14, s31, s0
	v_ashrrev_i32_e32 v3, 31, v2
	s_addc_u32 s15, s30, s1
	v_lshlrev_b64 v[2:3], 6, v[2:3]
	s_lshl_b64 s[14:15], s[14:15], 11
	v_lshl_add_u64 v[2:3], s[66:67], 0, v[2:3]
	v_mov_b32_e32 v16, v158
	s_add_u32 s14, s90, s14
	s_waitcnt vmcnt(63) expcnt(7) lgkmcnt(15)
	s_barrier
	global_load_dwordx4 v[66:69], v[2:3], off offset:48
	global_load_dwordx4 v[70:73], v[2:3], off offset:32
	global_load_dwordx4 v[74:77], v[2:3], off offset:16
	global_load_dwordx4 v[78:81], v[2:3], off
	s_addc_u32 s15, s91, s15
	v_ashrrev_i32_e32 v2, 3, v16
	v_lshrrev_b32_e32 v17, 4, v16
	v_ashrrev_i32_e32 v3, 31, v2
	v_xor_b32_e32 v0, v17, v16
	s_cmp_gt_i32 s37, 41
	v_lshlrev_b64 v[4:5], 11, v[2:3]
	v_lshlrev_b32_e32 v0, 4, v0
	v_lshl_add_u64 v[6:7], s[12:13], 0, v[4:5]
	v_and_b32_e32 v0, 0x70, v0
	v_lshlrev_b32_e32 v93, 4, v16
	s_cselect_b32 s12, 63, 0x7f
	v_lshl_add_u64 v[6:7], v[6:7], 0, v[0:1]
	v_lshl_add_u64 v[8:9], s[14:15], 0, v[0:1]
	v_add_u32_e32 v3, 0x4000, v93
	v_readfirstlane_b32 s13, v93
	v_and_b32_e32 v0, s12, v2
	s_mov_b32 m0, s13
	v_lshlrev_b32_e32 v0, 11, v0
	v_readfirstlane_b32 s13, v3
	v_add_u32_e32 v3, 0x1000, v93
	global_load_lds_dwordx4 v[6:7], off
	v_lshl_add_u64 v[10:11], v[8:9], 0, v[0:1]
	s_mov_b32 m0, s13
	s_mov_b64 s[14:15], 0x10000
	v_readfirstlane_b32 s13, v3
	v_add_u32_e32 v3, 32, v2
	global_load_lds_dwordx4 v[10:11], off
	v_lshl_add_u64 v[10:11], v[6:7], 0, s[14:15]
	s_mov_b32 m0, s13
	v_and_b32_e32 v3, s12, v3
	global_load_lds_dwordx4 v[10:11], off
	v_lshlrev_b32_e32 v10, 11, v3
	v_add_u32_e32 v3, 0x5000, v93
	v_mov_b32_e32 v11, v1
	v_readfirstlane_b32 s13, v3
	v_add_u32_e32 v3, 0x2000, v93
	v_lshl_add_u64 v[12:13], v[8:9], 0, v[10:11]
	s_mov_b32 m0, s13
	v_readfirstlane_b32 s13, v3
	global_load_lds_dwordx4 v[12:13], off
	v_lshl_add_u64 v[12:13], v[6:7], 0, s[60:61]
	s_mov_b32 m0, s13
	v_bitop3_b32 v3, v2, s12, 64 bitop3:0x48
	global_load_lds_dwordx4 v[12:13], off
	v_lshlrev_b32_e32 v12, 11, v3
	v_add_u32_e32 v3, 0x6000, v93
	v_mov_b32_e32 v13, v1
	v_readfirstlane_b32 s13, v3
	v_add_u32_e32 v3, 0x3000, v93
	v_add_u32_e32 v2, 0x60, v2
	v_lshl_add_u64 v[14:15], v[8:9], 0, v[12:13]
	s_mov_b32 m0, s13
	s_mov_b64 s[14:15], 0x30000
	v_readfirstlane_b32 s13, v3
	v_and_b32_e32 v2, s12, v2
	global_load_lds_dwordx4 v[14:15], off
	v_lshl_add_u64 v[6:7], v[6:7], 0, s[14:15]
	s_mov_b32 m0, s13
	v_lshlrev_b32_e32 v2, 11, v2
	v_mov_b32_e32 v3, v1
	global_load_lds_dwordx4 v[6:7], off
	v_lshl_add_u64 v[6:7], v[8:9], 0, v[2:3]
	v_add_u32_e32 v3, 0x7000, v93
	v_readfirstlane_b32 s11, v16
	v_readfirstlane_b32 s12, v3
	s_mov_b32 m0, s12
	s_lshl_b32 s12, s11, 7
	global_load_lds_dwordx4 v[6:7], off
	v_lshlrev_b32_e32 v3, 7, v16
	s_lshl_b32 s11, s11, 6
	v_bfe_u32 v18, v16, 4, 2
	v_bfe_u32 v20, v16, 1, 3
	s_and_b32 s12, s12, 0x2000
	v_and_b32_e32 v3, 0x780, v3
	s_and_b32 s11, s11, 0xffffe000
	v_or_b32_e32 v94, s12, v3
	v_or_b32_e32 v96, s11, v3
	v_bitop3_b32 v3, v18, v20, 4 bitop3:0x36
	v_lshlrev_b32_e32 v95, 4, v3
	v_bitop3_b32 v3, v17, 7, v16 bitop3:0x48
	v_lshlrev_b32_e32 v3, 4, v3
	v_or_b32_e32 v82, v4, v3
	s_lshl_b64 s[0:1], s[0:1], 11
	s_add_u32 s12, s74, s4
	s_addc_u32 s13, s75, s5
	v_readfirstlane_b32 s33, v93
	s_add_u32 s12, s12, 0x80
	s_addc_u32 s13, s13, 0
	v_add_u32_e32 v83, 0x10000, v82
	v_add_u32_e32 v84, 0x20000, v82
	v_add_u32_e32 v85, 0x30000, v82
	s_add_u32 s14, s2, s0
	s_addc_u32 s15, s3, s1
	v_or_b32_e32 v86, v0, v3
	v_or_b32_e32 v87, v10, v3
	v_lshrrev_b32_e32 v19, 1, v16
	v_or_b32_e32 v88, v12, v3
	v_bitop3_b32 v6, v19, v18, 7 bitop3:0x6c
	v_or_b32_e32 v89, v2, v3
	v_mov_b32_e32 v2, 0
	v_lshlrev_b32_e32 v97, 4, v6
	s_mov_b64 s[0:1], 0
	s_mov_b32 s4, 0
	v_mov_b32_e32 v3, v2
	v_mov_b32_e32 v4, v2
	v_mov_b32_e32 v5, v2
	v_mov_b32_e32 v6, v2
	v_mov_b32_e32 v7, v2
	v_mov_b32_e32 v8, v2
	v_mov_b32_e32 v9, v2
	v_mov_b32_e32 v10, v2
	v_mov_b32_e32 v11, v2
	v_mov_b32_e32 v12, v2
	v_mov_b32_e32 v13, v2
	v_mov_b32_e32 v14, v2
	v_mov_b32_e32 v15, v2
	v_mov_b32_e32 v16, v2
	v_mov_b32_e32 v17, v2
	v_mov_b32_e32 v18, v2
	v_mov_b32_e32 v19, v2
	v_mov_b32_e32 v20, v2
	v_mov_b32_e32 v21, v2
	v_mov_b32_e32 v22, v2
	v_mov_b32_e32 v23, v2
	v_mov_b32_e32 v24, v2
	v_mov_b32_e32 v25, v2
	v_mov_b32_e32 v26, v2
	v_mov_b32_e32 v27, v2
	v_mov_b32_e32 v28, v2
	v_mov_b32_e32 v29, v2
	v_mov_b32_e32 v30, v2
	v_mov_b32_e32 v31, v2
	v_mov_b32_e32 v32, v2
	v_mov_b32_e32 v33, v2
	v_mov_b32_e32 v34, v2
	v_mov_b32_e32 v35, v2
	v_mov_b32_e32 v36, v2
	v_mov_b32_e32 v37, v2
	v_mov_b32_e32 v38, v2
	v_mov_b32_e32 v39, v2
	v_mov_b32_e32 v40, v2
	v_mov_b32_e32 v41, v2
	v_mov_b32_e32 v42, v2
	v_mov_b32_e32 v43, v2
	v_mov_b32_e32 v44, v2
	v_mov_b32_e32 v45, v2
	v_mov_b32_e32 v46, v2
	v_mov_b32_e32 v47, v2
	v_mov_b32_e32 v48, v2
	v_mov_b32_e32 v49, v2
	v_mov_b32_e32 v50, v2
	v_mov_b32_e32 v51, v2
	v_mov_b32_e32 v52, v2
	v_mov_b32_e32 v53, v2
	v_mov_b32_e32 v54, v2
	v_mov_b32_e32 v55, v2
	v_mov_b32_e32 v56, v2
	v_mov_b32_e32 v57, v2
	v_mov_b32_e32 v58, v2
	v_mov_b32_e32 v59, v2
	v_mov_b32_e32 v60, v2
	v_mov_b32_e32 v61, v2
	v_mov_b32_e32 v62, v2
	v_mov_b32_e32 v63, v2
	v_mov_b32_e32 v64, v2
	v_mov_b32_e32 v65, v2
	s_waitcnt vmcnt(0) lgkmcnt(0)
	s_barrier
; #define MFMA16(a, b, c) __builtin_amdgcn_mfma_f32_16x16x32_bf16((a), (b), (c), 0, 0, 0)
; DI void gemm_tile(const bf16_t* __restrict__ A, int lda, const bf16_t* __restrict__ Bt, int ldb, int bvalid, int K, f32x4 (&acc)[4][4], char* lds, bool preloaded = false) {
;     ...
;   auto compute = [&](int st) {
;     const char* base = lds + st * 32768;
;     bf16x8 af[2][4], bfr[2][4];
; #pragma unroll
;     for (int s = 0; s < 2; ++s) {
;       const int ch = ((4 * s + fq) ^ fx) << 4;
; #pragma unroll
;       for (int mi = 0; mi < 4; ++mi) af[s][mi] = *(const bf16x8*)(base + (wm * 64 + mi * 16 + fr) * 128 + ch);
; #pragma unroll
;       for (int ni = 0; ni < 4; ++ni) bfr[s][ni] = *(const bf16x8*)(base + 16384 + (wn * 64 + ni * 16 + fr) * 128 + ch);
;     }
;     __builtin_amdgcn_s_setprio(1);
; #pragma unroll
;     for (int s = 0; s < 2; ++s)
; #pragma unroll
;       for (int mi = 0; mi < 4; ++mi)
; #pragma unroll
;         for (int ni = 0; ni < 4; ++ni) acc[mi][ni] = MFMA16(af[s][mi], bfr[s][ni], acc[mi][ni]);
;     __builtin_amdgcn_s_setprio(0);
;   };
;   const int nk = K >> 6;
;   if (!preloaded) { GLDS(0, 0) }
;   __syncthreads();
;   for (int kt = 0; kt < nk; ++kt) {
;     if (kt + 1 < nk) { GLDS((kt + 1) & 1, (kt + 1) << 6) }
;     compute(kt & 1);
;     __syncthreads();
;   }
.LBB0_1193:
	s_add_i32 s5, s4, 0x8000
	s_and_b32 s11, s5, 0x8000
	s_and_b32 s4, s4, 0x8000
	v_or_b32_e32 v0, s4, v97
	v_add_u32_e32 v110, v0, v96
	v_add_u32_e32 v0, v0, v94
	ds_read_b128 v[98:101], v110
	ds_read_b128 v[114:117], v0 offset:16384
	ds_read_b128 v[118:121], v0 offset:18432
	ds_read_b128 v[122:125], v0 offset:20480
	ds_read_b128 v[126:129], v0 offset:22528
	ds_read_b128 v[102:105], v110 offset:2048
	ds_read_b128 v[106:109], v110 offset:4096
	ds_read_b128 v[110:113], v110 offset:6144
	s_add_i32 m0, s33, s11
	v_or_b32_e32 v0, s4, v95
	global_load_lds_dwordx4 v82, s[12:13]
	s_addk_i32 m0, 0x1000
	v_add_u32_e32 v142, v0, v96
	global_load_lds_dwordx4 v83, s[12:13]
	s_addk_i32 m0, 0x1000
	v_add_u32_e32 v0, v0, v94
	global_load_lds_dwordx4 v84, s[12:13]
	s_addk_i32 m0, 0x1000
	ds_read_b128 v[130:133], v142
	global_load_lds_dwordx4 v85, s[12:13]
	s_addk_i32 m0, 0x1000
	ds_read_b128 v[146:149], v0 offset:16384
	global_load_lds_dwordx4 v86, s[14:15]
	s_addk_i32 m0, 0x1000
	ds_read_b128 v[150:153], v0 offset:18432
	global_load_lds_dwordx4 v87, s[14:15]
	s_addk_i32 m0, 0x1000
	ds_read_b128 v[154:157], v0 offset:20480
	global_load_lds_dwordx4 v88, s[14:15]
	s_addk_i32 m0, 0x1000
	ds_read_b128 v[180:183], v0 offset:22528
	global_load_lds_dwordx4 v89, s[14:15]
	ds_read_b128 v[134:137], v142 offset:2048
	ds_read_b128 v[138:141], v142 offset:4096
	ds_read_b128 v[142:145], v142 offset:6144
	s_add_u32 s12, s12, 0x80
	s_addc_u32 s13, s13, 0
	s_add_u32 s14, s14, 0x80
	s_addc_u32 s15, s15, 0
	s_setprio 1
	s_waitcnt lgkmcnt(14)
	v_mfma_f32_16x16x32_bf16 v[62:65], v[98:101], v[114:117], v[62:65]
	s_waitcnt lgkmcnt(13)
	v_mfma_f32_16x16x32_bf16 v[58:61], v[98:101], v[118:121], v[58:61]
	s_waitcnt lgkmcnt(12)
	v_mfma_f32_16x16x32_bf16 v[54:57], v[98:101], v[122:125], v[54:57]
	s_waitcnt lgkmcnt(11)
	v_mfma_f32_16x16x32_bf16 v[50:53], v[98:101], v[126:129], v[50:53]
	s_waitcnt lgkmcnt(10)
	v_mfma_f32_16x16x32_bf16 v[46:49], v[102:105], v[114:117], v[46:49]
	v_mfma_f32_16x16x32_bf16 v[42:45], v[102:105], v[118:121], v[42:45]
	v_mfma_f32_16x16x32_bf16 v[38:41], v[102:105], v[122:125], v[38:41]
	v_mfma_f32_16x16x32_bf16 v[34:37], v[102:105], v[126:129], v[34:37]
	s_waitcnt lgkmcnt(9)
	v_mfma_f32_16x16x32_bf16 v[30:33], v[106:109], v[114:117], v[30:33]
	v_mfma_f32_16x16x32_bf16 v[26:29], v[106:109], v[118:121], v[26:29]
	v_mfma_f32_16x16x32_bf16 v[22:25], v[106:109], v[122:125], v[22:25]
	v_mfma_f32_16x16x32_bf16 v[18:21], v[106:109], v[126:129], v[18:21]
	s_waitcnt lgkmcnt(8)
	v_mfma_f32_16x16x32_bf16 v[14:17], v[110:113], v[114:117], v[14:17]
	v_mfma_f32_16x16x32_bf16 v[10:13], v[110:113], v[118:121], v[10:13]
	v_mfma_f32_16x16x32_bf16 v[6:9], v[110:113], v[122:125], v[6:9]
	v_mfma_f32_16x16x32_bf16 v[2:5], v[110:113], v[126:129], v[2:5]
	s_waitcnt lgkmcnt(6)
	v_mfma_f32_16x16x32_bf16 v[62:65], v[130:133], v[146:149], v[62:65]
	s_waitcnt lgkmcnt(5)
	v_mfma_f32_16x16x32_bf16 v[58:61], v[130:133], v[150:153], v[58:61]
	s_waitcnt lgkmcnt(4)
	v_mfma_f32_16x16x32_bf16 v[54:57], v[130:133], v[154:157], v[54:57]
	s_waitcnt lgkmcnt(3)
	v_mfma_f32_16x16x32_bf16 v[50:53], v[130:133], v[180:183], v[50:53]
	s_waitcnt lgkmcnt(2)
	v_mfma_f32_16x16x32_bf16 v[46:49], v[134:137], v[146:149], v[46:49]
	v_mfma_f32_16x16x32_bf16 v[42:45], v[134:137], v[150:153], v[42:45]
	v_mfma_f32_16x16x32_bf16 v[38:41], v[134:137], v[154:157], v[38:41]
	v_mfma_f32_16x16x32_bf16 v[34:37], v[134:137], v[180:183], v[34:37]
	s_waitcnt lgkmcnt(1)
	v_mfma_f32_16x16x32_bf16 v[30:33], v[138:141], v[146:149], v[30:33]
	v_mfma_f32_16x16x32_bf16 v[26:29], v[138:141], v[150:153], v[26:29]
	v_mfma_f32_16x16x32_bf16 v[22:25], v[138:141], v[154:157], v[22:25]
	v_mfma_f32_16x16x32_bf16 v[18:21], v[138:141], v[180:183], v[18:21]
	s_waitcnt lgkmcnt(0)
	v_mfma_f32_16x16x32_bf16 v[14:17], v[142:145], v[146:149], v[14:17]
	v_mfma_f32_16x16x32_bf16 v[10:13], v[142:145], v[150:153], v[10:13]
	v_mfma_f32_16x16x32_bf16 v[6:9], v[142:145], v[154:157], v[6:9]
	v_mfma_f32_16x16x32_bf16 v[2:5], v[142:145], v[180:183], v[2:5]
	s_setprio 0
	s_add_u32 s0, s0, 0x80
	s_cmpk_eq_i32 s0, 0x780
	s_mov_b32 s4, s5
	s_waitcnt vmcnt(0)
	s_barrier
	s_cbranch_scc0 .LBB0_1193
; #define MFMA16(a, b, c) __builtin_amdgcn_mfma_f32_16x16x32_bf16((a), (b), (c), 0, 0, 0)
; DI void gemm_tile(const bf16_t* __restrict__ A, int lda, const bf16_t* __restrict__ Bt, int ldb, int bvalid, int K, f32x4 (&acc)[4][4], char* lds, bool preloaded = false) {
;     ...
;   auto compute = [&](int st) {
;     const char* base = lds + st * 32768;
;     bf16x8 af[2][4], bfr[2][4];
; #pragma unroll
;     for (int s = 0; s < 2; ++s) {
;       const int ch = ((4 * s + fq) ^ fx) << 4;
; #pragma unroll
;       for (int mi = 0; mi < 4; ++mi) af[s][mi] = *(const bf16x8*)(base + (wm * 64 + mi * 16 + fr) * 128 + ch);
; #pragma unroll
;       for (int ni = 0; ni < 4; ++ni) bfr[s][ni] = *(const bf16x8*)(base + 16384 + (wn * 64 + ni * 16 + fr) * 128 + ch);
;     }
;     __builtin_amdgcn_s_setprio(1);
; #pragma unroll
;     for (int s = 0; s < 2; ++s)
; #pragma unroll
;       for (int mi = 0; mi < 4; ++mi)
; #pragma unroll
;         for (int ni = 0; ni < 4; ++ni) acc[mi][ni] = MFMA16(af[s][mi], bfr[s][ni], acc[mi][ni]);
;     __builtin_amdgcn_s_setprio(0);
; DI void phaseA_tile(const P& p, int layer, int mt, int nt, char* lds) {
;     ...
;   if (tid < 128) {
;     const float ss = (ssa.x + ssa.y + ssa.z + ssa.w) + (ssb.x + ssb.y + ssb.z + ssb.w) + (ssc.x + ssc.y + ssc.z + ssc.w) + (ssd.x + ssd.y + ssd.z + ssd.w);
;     rr[tid] = rsqrtf(ss * (1.f / 1024.f) + 1e-6f);
;   }
	v_add_u32_e32 v0, v97, v96
	ds_read_b128 v[82:85], v0 offset:32768
	ds_read_b128 v[86:89], v0 offset:34816
	ds_read_b128 v[98:101], v0 offset:36864
	ds_read_b128 v[102:105], v0 offset:38912
	v_add_u32_e32 v0, v97, v94
	ds_read_b128 v[106:109], v0 offset:49152
	ds_read_b128 v[110:113], v0 offset:51200
	ds_read_b128 v[114:117], v0 offset:53248
	ds_read_b128 v[118:121], v0 offset:55296
	v_add_u32_e32 v0, v95, v96
	ds_read_b128 v[122:125], v0 offset:32768
	ds_read_b128 v[126:129], v0 offset:34816
	ds_read_b128 v[130:133], v0 offset:36864
	ds_read_b128 v[134:137], v0 offset:38912
	v_add_u32_e32 v0, v95, v94
	ds_read_b128 v[94:97], v0 offset:49152
	ds_read_b128 v[138:141], v0 offset:51200
	ds_read_b128 v[142:145], v0 offset:53248
	ds_read_b128 v[146:149], v0 offset:55296
	s_movk_i32 s33, 0x210
	v_readfirstlane_b32 s4, v92
	s_setprio 1
	s_waitcnt lgkmcnt(11)
	v_mfma_f32_16x16x32_bf16 v[62:65], v[82:85], v[106:109], v[62:65]
	s_waitcnt lgkmcnt(10)
	v_mfma_f32_16x16x32_bf16 v[58:61], v[82:85], v[110:113], v[58:61]
	s_waitcnt lgkmcnt(9)
	v_mfma_f32_16x16x32_bf16 v[54:57], v[82:85], v[114:117], v[54:57]
	s_waitcnt lgkmcnt(8)
	v_mfma_f32_16x16x32_bf16 v[50:53], v[82:85], v[118:121], v[50:53]
	v_mfma_f32_16x16x32_bf16 v[46:49], v[86:89], v[106:109], v[46:49]
	v_mfma_f32_16x16x32_bf16 v[42:45], v[86:89], v[110:113], v[42:45]
	v_mfma_f32_16x16x32_bf16 v[38:41], v[86:89], v[114:117], v[38:41]
	v_mfma_f32_16x16x32_bf16 v[34:37], v[86:89], v[118:121], v[34:37]
	v_mfma_f32_16x16x32_bf16 v[30:33], v[98:101], v[106:109], v[30:33]
	v_mfma_f32_16x16x32_bf16 v[26:29], v[98:101], v[110:113], v[26:29]
	v_mfma_f32_16x16x32_bf16 v[22:25], v[98:101], v[114:117], v[22:25]
	v_mfma_f32_16x16x32_bf16 v[18:21], v[98:101], v[118:121], v[18:21]
	v_mfma_f32_16x16x32_bf16 v[14:17], v[102:105], v[106:109], v[14:17]
	v_mfma_f32_16x16x32_bf16 v[10:13], v[102:105], v[110:113], v[10:13]
	v_mfma_f32_16x16x32_bf16 v[6:9], v[102:105], v[114:117], v[6:9]
	v_mfma_f32_16x16x32_bf16 v[2:5], v[102:105], v[118:121], v[2:5]
	s_waitcnt lgkmcnt(3)
	v_mfma_f32_16x16x32_bf16 v[62:65], v[122:125], v[94:97], v[62:65]
	s_waitcnt lgkmcnt(2)
	v_mfma_f32_16x16x32_bf16 v[58:61], v[122:125], v[138:141], v[58:61]
	s_waitcnt lgkmcnt(1)
	v_mfma_f32_16x16x32_bf16 v[54:57], v[122:125], v[142:145], v[54:57]
	s_waitcnt lgkmcnt(0)
	v_mfma_f32_16x16x32_bf16 v[50:53], v[122:125], v[146:149], v[50:53]
	v_mfma_f32_16x16x32_bf16 v[46:49], v[126:129], v[94:97], v[46:49]
	v_mfma_f32_16x16x32_bf16 v[42:45], v[126:129], v[138:141], v[42:45]
	v_mfma_f32_16x16x32_bf16 v[38:41], v[126:129], v[142:145], v[38:41]
	v_mfma_f32_16x16x32_bf16 v[34:37], v[126:129], v[146:149], v[34:37]
	v_mfma_f32_16x16x32_bf16 v[30:33], v[130:133], v[94:97], v[30:33]
	v_mfma_f32_16x16x32_bf16 v[26:29], v[130:133], v[138:141], v[26:29]
	v_mfma_f32_16x16x32_bf16 v[22:25], v[130:133], v[142:145], v[22:25]
	v_mfma_f32_16x16x32_bf16 v[18:21], v[130:133], v[146:149], v[18:21]
	v_mfma_f32_16x16x32_bf16 v[14:17], v[134:137], v[94:97], v[14:17]
	v_mfma_f32_16x16x32_bf16 v[10:13], v[134:137], v[138:141], v[10:13]
	v_mfma_f32_16x16x32_bf16 v[6:9], v[134:137], v[142:145], v[6:9]
	v_mfma_f32_16x16x32_bf16 v[2:5], v[134:137], v[146:149], v[2:5]
	s_setprio 0
	v_cmp_gt_i32_e32 vcc, s92, v92
	s_barrier
	s_and_saveexec_b64 s[0:1], vcc
	s_cbranch_execz .LBB0_1196
	v_mov_b32_e32 v82, v78
	v_mov_b32_e32 v83, v74
	v_mov_b32_e32 v74, v79
	v_pk_add_f32 v[74:75], v[82:83], v[74:75]
	v_mov_b32_e32 v78, v80
	v_mov_b32_e32 v79, v76
	v_pk_add_f32 v[74:75], v[78:79], v[74:75]
	v_mov_b32_e32 v76, v81
	v_pk_add_f32 v[74:75], v[76:77], v[74:75]
	v_mov_b32_e32 v76, v70
	v_mov_b32_e32 v77, v66
	v_mov_b32_e32 v66, v71
	v_pk_add_f32 v[66:67], v[76:77], v[66:67]
	v_mov_b32_e32 v70, v72
	v_mov_b32_e32 v71, v68
	v_pk_add_f32 v[66:67], v[70:71], v[66:67]
	v_mov_b32_e32 v68, v73
	v_pk_add_f32 v[66:67], v[68:69], v[66:67]
	v_add_f32_e32 v0, v74, v75
	v_add_f32_e32 v0, v0, v66
	v_add_f32_e32 v0, v0, v67
	v_fmamk_f32 v0, v0, 0x3a800000, v160
	s_mov_b32 s5, 0x800000
	v_mul_f32_e32 v66, 0x4b800000, v0
	v_cmp_gt_f32_e32 vcc, s5, v0
	s_nop 1
	v_cndmask_b32_e32 v0, v0, v66, vcc
	v_rsq_f32_e32 v0, v0
	s_nop 0
	v_mul_f32_e32 v66, 0x45800000, v0
	v_cndmask_b32_e32 v0, v0, v66, vcc
	v_lshl_add_u32 v66, v92, 2, v173
	ds_write_b32 v66, v0
